# attention row-max xor-32 exchange via v_permlane32_swap (plus DPP/permlane conv LayerNorm sums); no ds_bpermute on those critical paths
# baseline (speedup 1.0000x reference)
.LBB0_767:
	v_max3_f32 v0, v96, v97, v98
	v_max3_f32 v2, v112, v113, v114
	v_max3_f32 v0, v0, v99, v100
	v_max3_f32 v2, v2, v115, v116
	v_max3_f32 v0, v0, v101, v102
	v_max3_f32 v2, v2, v117, v118
	v_max3_f32 v0, v0, v103, v104
	v_max3_f32 v2, v2, v119, v120
	v_max3_f32 v0, v0, v105, v106
	v_max3_f32 v2, v2, v121, v122
	v_max3_f32 v0, v0, v107, v108
	v_max3_f32 v2, v2, v123, v124
	v_max3_f32 v0, v0, v109, v110
	v_max3_f32 v2, v2, v125, v126
	v_max_f32_e32 v0, v0, v111
	v_max_f32_e32 v2, v2, v127
	v_max3_f32 v3, v64, v65, v66
	v_max3_f32 v4, v80, v81, v82
	v_max3_f32 v3, v3, v67, v68
	v_max3_f32 v4, v4, v83, v84
	v_max3_f32 v3, v3, v69, v70
	v_max3_f32 v4, v4, v85, v86
	v_max3_f32 v3, v3, v71, v72
	v_max3_f32 v4, v4, v87, v88
	v_max3_f32 v3, v3, v73, v74
	v_max3_f32 v4, v4, v89, v90
	v_max3_f32 v3, v3, v75, v76
	v_max3_f32 v4, v4, v91, v92
	v_max3_f32 v3, v3, v77, v78
	v_max3_f32 v4, v4, v93, v94
	v_max_f32_e32 v3, v3, v79
	v_max_f32_e32 v4, v4, v95
	v_max3_f32 v0, v0, v2, v3
	v_max_f32_e32 v0, v0, v4
	v_mov_b32_e32 v2, v0
	s_nop 1
	v_permlane32_swap_b32 v0, v2
	s_waitcnt lgkmcnt(0)
	s_nop 0
	v_max_f32_e32 v0, v0, v2
	v_add_f32_e32 v2, 0x41000000, v208
	v_cmp_gt_f32_e32 vcc, v0, v2
	s_cbranch_vccz .LBB0_769
	v_max_f32_e32 v0, v0, v0
	v_max_f32_e32 v2, v208, v208
	v_max_f32_e32 v2, v2, v0
	v_cmp_neq_f32_e32 vcc, s54, v2
	s_nop 1
	v_cndmask_b32_e32 v0, 0, v2, vcc
	v_sub_f32_e32 v0, v208, v0
	v_exp_f32_e32 v0, v0
	v_mov_b32_e32 v208, v2
	v_pk_mul_f32 v[62:63], v[62:63], v[0:1] op_sel_hi:[1,0]
	v_pk_mul_f32 v[60:61], v[60:61], v[0:1] op_sel_hi:[1,0]
	v_pk_mul_f32 v[58:59], v[58:59], v[0:1] op_sel_hi:[1,0]
	v_pk_mul_f32 v[56:57], v[56:57], v[0:1] op_sel_hi:[1,0]
	v_pk_mul_f32 v[54:55], v[54:55], v[0:1] op_sel_hi:[1,0]
	v_pk_mul_f32 v[52:53], v[52:53], v[0:1] op_sel_hi:[1,0]
	v_pk_mul_f32 v[50:51], v[50:51], v[0:1] op_sel_hi:[1,0]
	v_pk_mul_f32 v[48:49], v[48:49], v[0:1] op_sel_hi:[1,0]
	v_pk_mul_f32 v[46:47], v[46:47], v[0:1] op_sel_hi:[1,0]
	v_pk_mul_f32 v[44:45], v[44:45], v[0:1] op_sel_hi:[1,0]
	v_pk_mul_f32 v[42:43], v[42:43], v[0:1] op_sel_hi:[1,0]
	v_pk_mul_f32 v[40:41], v[40:41], v[0:1] op_sel_hi:[1,0]
	v_pk_mul_f32 v[38:39], v[38:39], v[0:1] op_sel_hi:[1,0]
	v_pk_mul_f32 v[36:37], v[36:37], v[0:1] op_sel_hi:[1,0]
	v_pk_mul_f32 v[34:35], v[34:35], v[0:1] op_sel_hi:[1,0]
	v_pk_mul_f32 v[32:33], v[32:33], v[0:1] op_sel_hi:[1,0]
	v_mul_f32_e32 v225, v225, v0

.LBB0_823:
	v_max3_f32 v132, v96, v97, v98
	v_max3_f32 v133, v112, v113, v114
	v_max3_f32 v132, v132, v99, v100
	v_max3_f32 v133, v133, v115, v116
	v_max3_f32 v132, v132, v101, v102
	v_max3_f32 v133, v133, v117, v118
	v_max3_f32 v132, v132, v103, v104
	v_max3_f32 v133, v133, v119, v120
	v_max3_f32 v132, v132, v105, v106
	v_max3_f32 v133, v133, v121, v122
	v_max3_f32 v132, v132, v107, v108
	v_max3_f32 v133, v133, v123, v124
	v_max3_f32 v132, v132, v109, v110
	v_max3_f32 v133, v133, v125, v126
	v_max_f32_e32 v132, v132, v111
	v_max_f32_e32 v133, v133, v127
	v_max3_f32 v134, v64, v65, v66
	v_max3_f32 v135, v80, v81, v82
	v_max3_f32 v134, v134, v67, v68
	v_max3_f32 v135, v135, v83, v84
	v_max3_f32 v134, v134, v69, v70
	v_max3_f32 v135, v135, v85, v86
	v_max3_f32 v134, v134, v71, v72
	v_max3_f32 v135, v135, v87, v88
	v_max3_f32 v134, v134, v73, v74
	v_max3_f32 v135, v135, v89, v90
	v_max3_f32 v134, v134, v75, v76
	v_max3_f32 v135, v135, v91, v92
	v_max3_f32 v134, v134, v77, v78
	v_max3_f32 v135, v135, v93, v94
	v_max_f32_e32 v134, v134, v79
	v_max_f32_e32 v135, v135, v95
	v_max3_f32 v132, v132, v133, v134
	v_max_f32_e32 v132, v132, v135
	v_mov_b32_e32 v133, v132
	s_nop 1
	v_permlane32_swap_b32 v132, v133
	s_waitcnt lgkmcnt(0)
	s_nop 0
	v_max_f32_e32 v132, v132, v133
	v_add_f32_e32 v133, 0x41000000, v131
	v_cmp_gt_f32_e32 vcc, v132, v133
	s_cbranch_vccz .LBB0_825
	v_max_f32_e32 v132, v132, v132
	v_max_f32_e32 v133, v131, v131
	v_max_f32_e32 v133, v133, v132
	v_cmp_neq_f32_e32 vcc, s54, v133
	s_nop 1
	v_cndmask_b32_e32 v132, 0, v133, vcc
	v_sub_f32_e32 v131, v131, v132
	v_exp_f32_e32 v132, v131
	v_mov_b32_e32 v131, v133
	v_pk_mul_f32 v[62:63], v[62:63], v[132:133] op_sel_hi:[1,0]
	v_pk_mul_f32 v[60:61], v[60:61], v[132:133] op_sel_hi:[1,0]
	v_pk_mul_f32 v[58:59], v[58:59], v[132:133] op_sel_hi:[1,0]
	v_pk_mul_f32 v[56:57], v[56:57], v[132:133] op_sel_hi:[1,0]
	v_pk_mul_f32 v[54:55], v[54:55], v[132:133] op_sel_hi:[1,0]
	v_pk_mul_f32 v[52:53], v[52:53], v[132:133] op_sel_hi:[1,0]
	v_pk_mul_f32 v[50:51], v[50:51], v[132:133] op_sel_hi:[1,0]
	v_pk_mul_f32 v[48:49], v[48:49], v[132:133] op_sel_hi:[1,0]
	v_pk_mul_f32 v[46:47], v[46:47], v[132:133] op_sel_hi:[1,0]
	v_pk_mul_f32 v[44:45], v[44:45], v[132:133] op_sel_hi:[1,0]
	v_pk_mul_f32 v[42:43], v[42:43], v[132:133] op_sel_hi:[1,0]
	v_pk_mul_f32 v[40:41], v[40:41], v[132:133] op_sel_hi:[1,0]
	v_pk_mul_f32 v[38:39], v[38:39], v[132:133] op_sel_hi:[1,0]
	v_pk_mul_f32 v[36:37], v[36:37], v[132:133] op_sel_hi:[1,0]
	v_pk_mul_f32 v[34:35], v[34:35], v[132:133] op_sel_hi:[1,0]
	v_pk_mul_f32 v[32:33], v[32:33], v[132:133] op_sel_hi:[1,0]
	v_mul_f32_e32 v130, v130, v132
